# v79 + sub-phase boundary store drains removed: p2_diffattn entry vmcnt(0) (mlstm_u's trailing stores) and the P4 dec_out -> mlstm_out barrier's vmcnt(0)
# speedup vs baseline: 1.0154x; 1.0033x over previous
.LBB0_693:
	v_readlane_b32 s0, v245, 2
	v_readlane_b32 s1, v245, 3
	v_readlane_b32 s3, v245, 5
	s_bitcmp0_b32 s3, 1
	s_mov_b32 s1, 0
	v_readlane_b32 s2, v245, 4
	s_cbranch_scc1 .LBB0_788
	s_bfe_u32 s0, s92, 0x20003
	s_ashr_i32 s2, s92, 5
	s_bfe_u32 s6, s92, 0x10002
	s_lshl_b32 s7, s0, 1
	s_ashr_i32 s3, s2, 31
	s_or_b32 s6, s7, s6
	s_lshl_b64 s[4:5], s[2:3], 21
	s_lshl_b32 s7, s6, 7
	s_add_u32 s4, s96, s4
	s_addc_u32 s5, s97, s5
	s_add_u32 s7, s4, s7
	s_addc_u32 s9, s5, 0
	s_add_u32 s36, s7, 0xce00000
	s_addc_u32 s37, s9, 0
	s_add_u32 s8, s7, 0xde40000
	s_addc_u32 s9, s9, 0
	s_lshl_b32 s0, s0, 8
	s_add_u32 s0, s4, s0
	s_addc_u32 s4, s5, 0
	s_lshl_b32 s5, s92, 6
	s_and_b32 s5, s5, 0x80
	s_add_u32 s0, s0, s5
	s_addc_u32 s4, s4, 0
	s_add_u32 s10, s0, 0xee80000
	s_addc_u32 s11, s4, 0
	s_lshl_b64 s[2:3], s[2:3], 22
	s_add_u32 s0, s96, s2
	s_addc_u32 s2, s97, s3
	s_lshl_b32 s3, s6, 8
	s_add_u32 s0, s0, s3
	s_addc_u32 s2, s2, 0
	s_add_u32 s0, s0, s5
	s_addc_u32 s2, s2, 0
	s_add_u32 s38, s0, 0x19000000
	s_addc_u32 s39, s2, 0
	v_mov_b32_e32 v1, v0
	s_bitcmp1_b32 s92, 0
	s_cselect_b64 s[2:3], -1, 0
	v_cndmask_b32_e64 v1, 0, 1, s[2:3]
	v_mov_b32_e32 v3, 0
	s_mov_b32 s20, 0xffff0000
	v_cmp_ne_u32_e64 s[2:3], 1, v1
	s_mov_b64 s[12:13], 0x10000
	v_mov_b32_e32 v18, v3
	v_mov_b32_e32 v19, v3
	v_mov_b32_e32 v20, v3
	v_mov_b32_e32 v21, v3
	v_mov_b32_e32 v22, v3
	v_mov_b32_e32 v23, v3
	v_mov_b32_e32 v24, v3
	v_mov_b32_e32 v25, v3
	v_mov_b32_e32 v26, v3
	v_mov_b32_e32 v27, v3
	v_mov_b32_e32 v28, v3
	v_mov_b32_e32 v29, v3
	v_mov_b32_e32 v30, v3
	v_mov_b32_e32 v31, v3
	v_mov_b32_e32 v32, v3
	v_mov_b32_e32 v33, v3
	s_mov_b64 s[14:15], 0x20000
	s_mov_b64 s[16:17], 0x30000
	s_mov_b32 s21, -1
	s_mov_b32 s40, 0x41000000
	v_mov_b32_e32 v1, 0xff800000
	s_mov_b32 s41, 0
	s_branch .LBB0_696

.LBB0_1034:
	v_mov_b32_e32 v1, v0
	s_waitcnt lgkmcnt(0)
	s_barrier
	v_readlane_b32 s8, v245, 2
	v_readfirstlane_b32 s1, v1
	s_ashr_i32 s0, s1, 6
	s_cmp_lt_u32 s0, 2
	v_mov_b32_e32 v2, 0
	v_readlane_b32 s11, v245, 5
	v_readlane_b32 s9, v245, 3
	v_readlane_b32 s10, v245, 4
	s_cbranch_scc1 .LBB0_1047
	s_cmp_lt_i32 s0, 4
	s_cbranch_scc1 .LBB0_1039
	s_mov_b64 s[4:5], 0
	s_mov_b32 s6, 1
	s_cmp_gt_i32 s0, 4
	s_mov_b64 s[2:3], 0
	s_cbranch_scc0 .LBB0_1040
	s_cmp_eq_u32 s0, 5
	s_cbranch_scc0 .LBB0_1129
	s_mov_b32 s6, 2
	s_and_b64 vcc, exec, s[4:5]
	s_cbranch_vccnz .LBB0_1041
	s_branch .LBB0_1045
